# grid barrier: waiting workgroups poll the top-level arrival counter (released at (generation+1)*nXCD); the last arriver no longer publishes a separate generation word
# speedup vs baseline: 1.0018x; 1.0018x over previous
.LBB0_272:
	s_lshl_b32 s20, s28, 6
	s_add_i32 s2, s20, 0x500
	s_mov_b32 s3, 0
	s_lshl_b64 s[0:1], s[2:3], 2
	s_add_u32 s0, s34, s0
	s_addc_u32 s1, s35, s1
	v_mov_b32_e32 v1, 1
	v_mov_b64_e32 v[4:5], s[0:1]
	flat_atomic_add v1, v[4:5], v1 sc0
	buffer_inv sc1
	v_cvt_f32_u32_e32 v3, v2
	v_sub_u32_e32 v4, 0, v2
	v_rcp_iflag_f32_e32 v3, v3
	s_nop 0
	v_mul_f32_e32 v3, 0x4f7ffffe, v3
	v_cvt_u32_f32_e32 v3, v3
	v_mul_lo_u32 v4, v4, v3
	v_mul_hi_u32 v4, v3, v4
	v_add_u32_e32 v3, v3, v4
	s_waitcnt vmcnt(0) lgkmcnt(0)
	v_mul_hi_u32 v3, v1, v3
	v_mul_lo_u32 v5, v3, v2
	v_add_u32_e32 v4, 1, v1
	v_sub_u32_e32 v1, v1, v5
	v_add_u32_e32 v6, 1, v3
	v_cmp_ge_u32_e32 vcc, v1, v2
	v_sub_u32_e32 v5, v1, v2
	s_nop 0
	v_cndmask_b32_e32 v3, v3, v6, vcc
	v_cndmask_b32_e32 v1, v1, v5, vcc
	v_add_u32_e32 v5, 1, v3
	v_cmp_ge_u32_e32 vcc, v1, v2
	s_nop 1
	v_cndmask_b32_e32 v1, v3, v5, vcc
	v_mad_u64_u32 v[2:3], s[0:1], v2, v1, v[2:3]
	v_cmp_ne_u32_e32 vcc, v4, v2
	s_and_saveexec_b64 s[0:1], vcc
	s_xor_b64 s[0:1], exec, s[0:1]
	s_cbranch_execz .LBB0_285
	s_movk_i32 s2, 0xd00
	s_lshl_b64 s[2:3], s[2:3], 2
	s_add_u32 s4, s34, s2
	s_addc_u32 s5, s35, s3
	v_mov_b64_e32 v[2:3], s[4:5]
	v_add_u32_e32 v7, 1, v1
	v_mul_lo_u32 v7, v7, v0
	flat_load_dword v0, v[2:3] sc1
	s_waitcnt vmcnt(0) lgkmcnt(0)
	v_cmp_lt_u32_e32 vcc, v0, v7
	s_and_saveexec_b64 s[2:3], vcc
	s_cbranch_execz .LBB0_284
	s_mov_b32 s21, 1
	s_mov_b64 s[6:7], 0
	s_branch .LBB0_276

.LBB0_280:
	s_andn2_b64 s[10:11], s[10:11], exec
	s_and_b64 s[16:17], s[16:17], exec
	s_or_b64 s[10:11], s[10:11], s[16:17]
	s_and_saveexec_b64 s[16:17], s[14:15]
	s_cbranch_execz .LBB0_275
	v_mov_b64_e32 v[2:3], s[4:5]
	flat_load_dword v0, v[2:3] sc1
	s_add_i32 s21, s21, 1
	s_or_b64 s[10:11], s[10:11], exec
	s_waitcnt vmcnt(0) lgkmcnt(0)
	v_cmp_ge_u32_e32 vcc, v0, v7
	s_orn2_b64 s[12:13], vcc, exec
	s_branch .LBB0_275

.LBB0_285:
	s_andn2_saveexec_b64 s[0:1], s[0:1]
	s_cbranch_execz .LBB0_301
	v_mov_b32_e32 v1, s34
	v_add_co_u32_e32 v2, vcc, 0x3000, v1
	v_mov_b32_e32 v1, s35
	buffer_wbl2 sc1
	s_waitcnt vmcnt(0)
	v_addc_co_u32_e32 v3, vcc, 0, v1, vcc
	v_mov_b32_e32 v1, 1
	flat_atomic_add v1, v[2:3], v1 offset:1024 sc0
	v_cvt_f32_u32_e32 v2, v0
	v_sub_u32_e32 v3, 0, v0
	s_add_u32 s0, s34, 0x3400
	s_addc_u32 s1, s35, 0
	v_rcp_iflag_f32_e32 v2, v2
	s_mov_b64 s[4:5], 0
	v_mul_f32_e32 v2, 0x4f7ffffe, v2
	v_cvt_u32_f32_e32 v2, v2
	v_mul_lo_u32 v3, v3, v2
	v_mul_hi_u32 v3, v2, v3
	v_add_u32_e32 v2, v2, v3
	s_waitcnt vmcnt(0) lgkmcnt(0)
	v_mul_hi_u32 v2, v1, v2
	v_mul_lo_u32 v4, v2, v0
	v_add_u32_e32 v3, 1, v1
	v_sub_u32_e32 v1, v1, v4
	v_add_u32_e32 v5, 1, v2
	v_cmp_ge_u32_e32 vcc, v1, v0
	v_sub_u32_e32 v4, v1, v0
	s_nop 0
	v_cndmask_b32_e32 v2, v2, v5, vcc
	v_cndmask_b32_e32 v1, v1, v4, vcc
	v_add_u32_e32 v4, 1, v2
	v_cmp_ge_u32_e32 vcc, v1, v0
	s_nop 1
	v_cndmask_b32_e32 v2, v2, v4, vcc
	v_mad_u64_u32 v[0:1], s[2:3], v0, v2, v[0:1]
	v_mov_b32_e32 v7, v0
	v_cmp_ne_u32_e32 vcc, v3, v0
	v_mov_b64_e32 v[0:1], s[0:1]
	s_and_saveexec_b64 s[2:3], vcc
	s_cbranch_execz .LBB0_298
	v_mov_b64_e32 v[0:1], s[0:1]
	flat_load_dword v0, v[0:1] sc1
	s_mov_b64 s[8:9], 0
	s_waitcnt vmcnt(0) lgkmcnt(0)
	v_cmp_lt_u32_e32 vcc, v0, v7
	s_and_saveexec_b64 s[6:7], vcc
	s_cbranch_execz .LBB0_297
	s_add_u32 s4, s34, 0x200
	s_addc_u32 s5, s35, 0
	s_mov_b32 s21, 1
	s_branch .LBB0_290

.LBB0_295:
	v_mov_b64_e32 v[0:1], s[0:1]
	flat_load_dword v0, v[0:1] sc1
	s_add_i32 s21, s21, 1
	s_or_b64 s[12:13], s[12:13], exec
	s_waitcnt vmcnt(0) lgkmcnt(0)
	v_cmp_ge_u32_e32 vcc, v0, v7
	s_orn2_b64 s[16:17], vcc, exec
	s_branch .LBB0_289

.LBB0_401:
	s_lshl_b32 s20, s28, 6
	s_add_i32 s38, s20, 0x500
	s_lshl_b64 s[0:1], s[38:39], 2
	s_add_u32 s0, s54, s0
	s_addc_u32 s1, s55, s1
	v_mov_b64_e32 v[4:5], s[0:1]
	flat_atomic_add v3, v[4:5], v249 sc0
	buffer_inv sc1
	v_cvt_f32_u32_e32 v1, v2
	v_sub_u32_e32 v4, 0, v2
	v_rcp_iflag_f32_e32 v1, v1
	s_nop 0
	v_mul_f32_e32 v1, 0x4f7ffffe, v1
	v_cvt_u32_f32_e32 v1, v1
	v_mul_lo_u32 v4, v4, v1
	v_mul_hi_u32 v4, v1, v4
	v_add_u32_e32 v1, v1, v4
	s_waitcnt vmcnt(0) lgkmcnt(0)
	v_mul_hi_u32 v1, v3, v1
	v_mul_lo_u32 v4, v1, v2
	v_sub_u32_e32 v4, v3, v4
	v_cmp_ge_u32_e32 vcc, v4, v2
	v_add_u32_e32 v5, 1, v1
	s_nop 0
	v_cndmask_b32_e32 v1, v1, v5, vcc
	v_sub_u32_e32 v5, v4, v2
	v_cndmask_b32_e32 v4, v4, v5, vcc
	v_cmp_ge_u32_e32 vcc, v4, v2
	v_add_u32_e32 v4, 1, v1
	s_nop 0
	v_cndmask_b32_e32 v1, v1, v4, vcc
	v_add_u32_e32 v4, 1, v3
	v_mad_u64_u32 v[2:3], s[0:1], v2, v1, v[2:3]
	v_cmp_ne_u32_e32 vcc, v4, v2
	s_and_saveexec_b64 s[0:1], vcc
	s_xor_b64 s[0:1], exec, s[0:1]
	s_cbranch_execz .LBB0_414
	s_movk_i32 s38, 0xd00
	s_lshl_b64 s[2:3], s[38:39], 2
	s_add_u32 s4, s54, s2
	s_addc_u32 s5, s55, s3
	v_mov_b64_e32 v[2:3], s[4:5]
	v_add_u32_e32 v7, 1, v1
	v_mul_lo_u32 v7, v7, v0
	flat_load_dword v0, v[2:3] sc1
	s_waitcnt vmcnt(0) lgkmcnt(0)
	v_cmp_lt_u32_e32 vcc, v0, v7
	s_and_saveexec_b64 s[2:3], vcc
	s_cbranch_execz .LBB0_413
	s_mov_b32 s21, 1
	s_mov_b64 s[6:7], 0
	s_branch .LBB0_405

.LBB0_414:
	s_andn2_saveexec_b64 s[0:1], s[0:1]
	s_cbranch_execz .LBB0_430
	v_mov_b32_e32 v1, s54
	v_add_co_u32_e32 v2, vcc, 0x3000, v1
	v_mov_b32_e32 v1, s55
	buffer_wbl2 sc1
	s_waitcnt vmcnt(0)
	v_addc_co_u32_e32 v3, vcc, 0, v1, vcc
	flat_atomic_add v1, v[2:3], v249 offset:1024 sc0
	v_cvt_f32_u32_e32 v2, v0
	v_sub_u32_e32 v3, 0, v0
	s_mov_b64 s[4:5], 0
	v_rcp_iflag_f32_e32 v2, v2
	s_nop 0
	v_mul_f32_e32 v2, 0x4f7ffffe, v2
	v_cvt_u32_f32_e32 v2, v2
	v_mul_lo_u32 v3, v3, v2
	v_mul_hi_u32 v3, v2, v3
	v_add_u32_e32 v2, v2, v3
	s_waitcnt vmcnt(0) lgkmcnt(0)
	v_mul_hi_u32 v2, v1, v2
	v_mul_lo_u32 v3, v2, v0
	v_sub_u32_e32 v3, v1, v3
	v_cmp_ge_u32_e32 vcc, v3, v0
	v_add_u32_e32 v4, 1, v2
	s_nop 0
	v_cndmask_b32_e32 v2, v2, v4, vcc
	v_sub_u32_e32 v4, v3, v0
	v_cndmask_b32_e32 v3, v3, v4, vcc
	v_cmp_ge_u32_e32 vcc, v3, v0
	v_add_u32_e32 v3, 1, v2
	s_nop 0
	v_cndmask_b32_e32 v2, v2, v3, vcc
	v_add_u32_e32 v3, 1, v1
	v_mad_u64_u32 v[0:1], s[0:1], v0, v2, v[0:1]
	v_mov_b32_e32 v7, v0
	s_add_u32 s0, s54, 0x3400
	s_addc_u32 s1, s55, 0
	v_cmp_ne_u32_e32 vcc, v3, v0
	v_mov_b64_e32 v[0:1], s[0:1]
	s_and_saveexec_b64 s[2:3], vcc
	s_cbranch_execz .LBB0_427
	v_mov_b64_e32 v[0:1], s[0:1]
	flat_load_dword v0, v[0:1] sc1
	s_mov_b64 s[8:9], 0
	s_waitcnt vmcnt(0) lgkmcnt(0)
	v_cmp_lt_u32_e32 vcc, v0, v7
	s_and_saveexec_b64 s[6:7], vcc
	s_cbranch_execz .LBB0_426
	s_add_u32 s4, s54, 0x200
	s_addc_u32 s5, s55, 0
	s_mov_b32 s21, 1
	s_branch .LBB0_419

.LBB0_424:
	v_mov_b64_e32 v[0:1], s[0:1]
	flat_load_dword v0, v[0:1] sc1
	s_add_i32 s21, s21, 1
	s_or_b64 s[14:15], s[14:15], exec
	s_waitcnt vmcnt(0) lgkmcnt(0)
	v_cmp_ge_u32_e32 vcc, v0, v7
	s_orn2_b64 s[12:13], vcc, exec
	s_branch .LBB0_418

.LBB0_628:
	s_lshl_b32 s20, s28, 6
	s_add_i32 s38, s20, 0x500
	s_lshl_b64 s[0:1], s[38:39], 2
	s_add_u32 s0, s34, s0
	s_addc_u32 s1, s35, s1
	v_mov_b64_e32 v[4:5], s[0:1]
	flat_atomic_add v3, v[4:5], v249 sc0
	buffer_inv sc1
	v_cvt_f32_u32_e32 v1, v2
	v_sub_u32_e32 v4, 0, v2
	v_rcp_iflag_f32_e32 v1, v1
	s_nop 0
	v_mul_f32_e32 v1, 0x4f7ffffe, v1
	v_cvt_u32_f32_e32 v1, v1
	v_mul_lo_u32 v4, v4, v1
	v_mul_hi_u32 v4, v1, v4
	v_add_u32_e32 v1, v1, v4
	s_waitcnt vmcnt(0) lgkmcnt(0)
	v_mul_hi_u32 v1, v3, v1
	v_mul_lo_u32 v4, v1, v2
	v_sub_u32_e32 v4, v3, v4
	v_cmp_ge_u32_e32 vcc, v4, v2
	v_add_u32_e32 v5, 1, v1
	s_nop 0
	v_cndmask_b32_e32 v1, v1, v5, vcc
	v_sub_u32_e32 v5, v4, v2
	v_cndmask_b32_e32 v4, v4, v5, vcc
	v_cmp_ge_u32_e32 vcc, v4, v2
	v_add_u32_e32 v4, 1, v1
	s_nop 0
	v_cndmask_b32_e32 v1, v1, v4, vcc
	v_add_u32_e32 v4, 1, v3
	v_mad_u64_u32 v[2:3], s[0:1], v2, v1, v[2:3]
	v_cmp_ne_u32_e32 vcc, v4, v2
	s_and_saveexec_b64 s[0:1], vcc
	s_xor_b64 s[0:1], exec, s[0:1]
	s_cbranch_execz .LBB0_641
	s_movk_i32 s38, 0xd00
	s_lshl_b64 s[2:3], s[38:39], 2
	s_add_u32 s4, s34, s2
	s_addc_u32 s5, s35, s3
	v_mov_b64_e32 v[2:3], s[4:5]
	v_add_u32_e32 v7, 1, v1
	v_mul_lo_u32 v7, v7, v0
	flat_load_dword v0, v[2:3] sc1
	s_waitcnt vmcnt(0) lgkmcnt(0)
	v_cmp_lt_u32_e32 vcc, v0, v7
	s_and_saveexec_b64 s[2:3], vcc
	s_cbranch_execz .LBB0_640
	s_mov_b32 s21, 1
	s_mov_b64 s[6:7], 0
	s_branch .LBB0_632

.LBB0_641:
	s_andn2_saveexec_b64 s[0:1], s[0:1]
	s_cbranch_execz .LBB0_657
	v_mov_b32_e32 v1, s34
	v_add_co_u32_e32 v2, vcc, 0x3000, v1
	v_mov_b32_e32 v1, s35
	buffer_wbl2 sc1
	s_waitcnt vmcnt(0)
	v_addc_co_u32_e32 v3, vcc, 0, v1, vcc
	flat_atomic_add v1, v[2:3], v249 offset:1024 sc0
	v_cvt_f32_u32_e32 v2, v0
	v_sub_u32_e32 v3, 0, v0
	s_mov_b64 s[4:5], 0
	v_rcp_iflag_f32_e32 v2, v2
	s_nop 0
	v_mul_f32_e32 v2, 0x4f7ffffe, v2
	v_cvt_u32_f32_e32 v2, v2
	v_mul_lo_u32 v3, v3, v2
	v_mul_hi_u32 v3, v2, v3
	v_add_u32_e32 v2, v2, v3
	s_waitcnt vmcnt(0) lgkmcnt(0)
	v_mul_hi_u32 v2, v1, v2
	v_mul_lo_u32 v3, v2, v0
	v_sub_u32_e32 v3, v1, v3
	v_cmp_ge_u32_e32 vcc, v3, v0
	v_add_u32_e32 v4, 1, v2
	s_nop 0
	v_cndmask_b32_e32 v2, v2, v4, vcc
	v_sub_u32_e32 v4, v3, v0
	v_cndmask_b32_e32 v3, v3, v4, vcc
	v_cmp_ge_u32_e32 vcc, v3, v0
	v_add_u32_e32 v3, 1, v2
	s_nop 0
	v_cndmask_b32_e32 v2, v2, v3, vcc
	v_add_u32_e32 v3, 1, v1
	v_mad_u64_u32 v[0:1], s[0:1], v0, v2, v[0:1]
	v_mov_b32_e32 v7, v0
	s_add_u32 s0, s34, 0x3400
	s_addc_u32 s1, s35, 0
	v_cmp_ne_u32_e32 vcc, v3, v0
	v_mov_b64_e32 v[0:1], s[0:1]
	s_and_saveexec_b64 s[2:3], vcc
	s_cbranch_execz .LBB0_654
	v_mov_b64_e32 v[0:1], s[0:1]
	flat_load_dword v0, v[0:1] sc1
	s_mov_b64 s[8:9], 0
	s_waitcnt vmcnt(0) lgkmcnt(0)
	v_cmp_lt_u32_e32 vcc, v0, v7
	s_and_saveexec_b64 s[6:7], vcc
	s_cbranch_execz .LBB0_653
	s_add_u32 s4, s34, 0x200
	s_addc_u32 s5, s35, 0
	s_mov_b32 s21, 1
	s_branch .LBB0_646

.LBB0_1713:
	s_lshl_b32 s0, s0, 6
	s_add_i32 s38, s0, 0x500
	s_lshl_b64 s[2:3], s[38:39], 2
	s_add_u32 s2, s56, s2
	s_addc_u32 s3, s57, s3
	v_mov_b64_e32 v[4:5], s[2:3]
	flat_atomic_add v3, v[4:5], v249 sc0
	buffer_inv sc1
	v_cvt_f32_u32_e32 v1, v2
	v_sub_u32_e32 v4, 0, v2
	v_rcp_iflag_f32_e32 v1, v1
	s_nop 0
	v_mul_f32_e32 v1, 0x4f7ffffe, v1
	v_cvt_u32_f32_e32 v1, v1
	v_mul_lo_u32 v4, v4, v1
	v_mul_hi_u32 v4, v1, v4
	v_add_u32_e32 v1, v1, v4
	s_waitcnt vmcnt(0) lgkmcnt(0)
	v_mul_hi_u32 v1, v3, v1
	v_mul_lo_u32 v4, v1, v2
	v_sub_u32_e32 v4, v3, v4
	v_cmp_ge_u32_e32 vcc, v4, v2
	v_add_u32_e32 v5, 1, v1
	s_nop 0
	v_cndmask_b32_e32 v1, v1, v5, vcc
	v_sub_u32_e32 v5, v4, v2
	v_cndmask_b32_e32 v4, v4, v5, vcc
	v_cmp_ge_u32_e32 vcc, v4, v2
	v_add_u32_e32 v4, 1, v1
	s_nop 0
	v_cndmask_b32_e32 v1, v1, v4, vcc
	v_add_u32_e32 v4, 1, v3
	v_mad_u64_u32 v[2:3], s[2:3], v2, v1, v[2:3]
	v_cmp_ne_u32_e32 vcc, v4, v2
	s_and_saveexec_b64 s[2:3], vcc
	s_xor_b64 s[2:3], exec, s[2:3]
	s_cbranch_execz .LBB0_1726
	s_movk_i32 s38, 0xd00
	s_lshl_b64 s[4:5], s[38:39], 2
	s_add_u32 s6, s56, s4
	s_addc_u32 s7, s57, s5
	v_mov_b64_e32 v[2:3], s[6:7]
	v_add_u32_e32 v7, 1, v1
	v_mul_lo_u32 v7, v7, v0
	flat_load_dword v0, v[2:3] sc1
	s_waitcnt vmcnt(0) lgkmcnt(0)
	v_cmp_lt_u32_e32 vcc, v0, v7
	s_and_saveexec_b64 s[4:5], vcc
	s_cbranch_execz .LBB0_1725
	s_mov_b32 s1, 1
	s_mov_b64 s[8:9], 0
	s_branch .LBB0_1717

.LBB0_1721:
	s_andn2_b64 s[12:13], s[12:13], exec
	s_and_b64 s[18:19], s[18:19], exec
	s_or_b64 s[12:13], s[12:13], s[18:19]
	s_and_saveexec_b64 s[18:19], s[16:17]
	s_cbranch_execz .LBB0_1716
	v_mov_b64_e32 v[2:3], s[6:7]
	flat_load_dword v0, v[2:3] sc1
	s_add_i32 s1, s1, 1
	s_or_b64 s[12:13], s[12:13], exec
	s_waitcnt vmcnt(0) lgkmcnt(0)
	v_cmp_ge_u32_e32 vcc, v0, v7
	s_orn2_b64 s[14:15], vcc, exec
	s_branch .LBB0_1716

.LBB0_1726:
	s_andn2_saveexec_b64 s[2:3], s[2:3]
	s_cbranch_execz .LBB0_1742
	v_mov_b32_e32 v1, s56
	v_add_co_u32_e32 v2, vcc, 0x3000, v1
	v_mov_b32_e32 v1, s57
	buffer_wbl2 sc1
	s_waitcnt vmcnt(0)
	v_addc_co_u32_e32 v3, vcc, 0, v1, vcc
	flat_atomic_add v1, v[2:3], v249 offset:1024 sc0
	v_cvt_f32_u32_e32 v2, v0
	v_sub_u32_e32 v3, 0, v0
	s_mov_b64 s[6:7], 0
	v_rcp_iflag_f32_e32 v2, v2
	s_nop 0
	v_mul_f32_e32 v2, 0x4f7ffffe, v2
	v_cvt_u32_f32_e32 v2, v2
	v_mul_lo_u32 v3, v3, v2
	v_mul_hi_u32 v3, v2, v3
	v_add_u32_e32 v2, v2, v3
	s_waitcnt vmcnt(0) lgkmcnt(0)
	v_mul_hi_u32 v2, v1, v2
	v_mul_lo_u32 v3, v2, v0
	v_sub_u32_e32 v3, v1, v3
	v_cmp_ge_u32_e32 vcc, v3, v0
	v_add_u32_e32 v4, 1, v2
	s_nop 0
	v_cndmask_b32_e32 v2, v2, v4, vcc
	v_sub_u32_e32 v4, v3, v0
	v_cndmask_b32_e32 v3, v3, v4, vcc
	v_cmp_ge_u32_e32 vcc, v3, v0
	v_add_u32_e32 v3, 1, v2
	s_nop 0
	v_cndmask_b32_e32 v2, v2, v3, vcc
	v_add_u32_e32 v3, 1, v1
	v_mad_u64_u32 v[0:1], s[2:3], v0, v2, v[0:1]
	v_mov_b32_e32 v7, v0
	s_add_u32 s2, s56, 0x3400
	s_addc_u32 s3, s57, 0
	v_cmp_ne_u32_e32 vcc, v3, v0
	v_mov_b64_e32 v[0:1], s[2:3]
	s_and_saveexec_b64 s[4:5], vcc
	s_cbranch_execz .LBB0_1739
	v_mov_b64_e32 v[0:1], s[2:3]
	flat_load_dword v0, v[0:1] sc1
	s_mov_b64 s[10:11], 0
	s_waitcnt vmcnt(0) lgkmcnt(0)
	v_cmp_lt_u32_e32 vcc, v0, v7
	s_and_saveexec_b64 s[8:9], vcc
	s_cbranch_execz .LBB0_1738
	s_add_u32 s6, s56, 0x200
	s_addc_u32 s7, s57, 0
	s_mov_b32 s1, 1
	s_branch .LBB0_1731

.LBB0_1736:
	v_mov_b64_e32 v[0:1], s[2:3]
	flat_load_dword v0, v[0:1] sc1
	s_add_i32 s1, s1, 1
	s_or_b64 s[16:17], s[16:17], exec
	s_waitcnt vmcnt(0) lgkmcnt(0)
	v_cmp_ge_u32_e32 vcc, v0, v7
	s_orn2_b64 s[14:15], vcc, exec
	s_branch .LBB0_1730

.LBB0_1851:
	s_lshl_b32 s0, s0, 6
	s_add_i32 s38, s0, 0x500
	s_lshl_b64 s[2:3], s[38:39], 2
	s_add_u32 s2, s62, s2
	s_addc_u32 s3, s63, s3
	v_mov_b64_e32 v[4:5], s[2:3]
	flat_atomic_add v3, v[4:5], v249 sc0
	buffer_inv sc1
	v_cvt_f32_u32_e32 v1, v2
	v_sub_u32_e32 v4, 0, v2
	v_rcp_iflag_f32_e32 v1, v1
	s_nop 0
	v_mul_f32_e32 v1, 0x4f7ffffe, v1
	v_cvt_u32_f32_e32 v1, v1
	v_mul_lo_u32 v4, v4, v1
	v_mul_hi_u32 v4, v1, v4
	v_add_u32_e32 v1, v1, v4
	s_waitcnt vmcnt(0) lgkmcnt(0)
	v_mul_hi_u32 v1, v3, v1
	v_mul_lo_u32 v4, v1, v2
	v_sub_u32_e32 v4, v3, v4
	v_cmp_ge_u32_e32 vcc, v4, v2
	v_add_u32_e32 v5, 1, v1
	s_nop 0
	v_cndmask_b32_e32 v1, v1, v5, vcc
	v_sub_u32_e32 v5, v4, v2
	v_cndmask_b32_e32 v4, v4, v5, vcc
	v_cmp_ge_u32_e32 vcc, v4, v2
	v_add_u32_e32 v4, 1, v1
	s_nop 0
	v_cndmask_b32_e32 v1, v1, v4, vcc
	v_add_u32_e32 v4, 1, v3
	v_mad_u64_u32 v[2:3], s[2:3], v2, v1, v[2:3]
	v_cmp_ne_u32_e32 vcc, v4, v2
	s_and_saveexec_b64 s[2:3], vcc
	s_xor_b64 s[2:3], exec, s[2:3]
	s_cbranch_execz .LBB0_1864
	s_movk_i32 s38, 0xd00
	s_lshl_b64 s[4:5], s[38:39], 2
	s_add_u32 s6, s62, s4
	s_addc_u32 s7, s63, s5
	v_mov_b64_e32 v[2:3], s[6:7]
	v_add_u32_e32 v7, 1, v1
	v_mul_lo_u32 v7, v7, v0
	flat_load_dword v0, v[2:3] sc1
	s_waitcnt vmcnt(0) lgkmcnt(0)
	v_cmp_lt_u32_e32 vcc, v0, v7
	s_and_saveexec_b64 s[4:5], vcc
	s_cbranch_execz .LBB0_1863
	s_mov_b32 s1, 1
	s_mov_b64 s[8:9], 0
	s_branch .LBB0_1855

.LBB0_1864:
	s_andn2_saveexec_b64 s[2:3], s[2:3]
	s_cbranch_execz .LBB0_1880
	v_mov_b32_e32 v1, s62
	v_add_co_u32_e32 v2, vcc, 0x3000, v1
	v_mov_b32_e32 v1, s63
	buffer_wbl2 sc1
	s_waitcnt vmcnt(0)
	v_addc_co_u32_e32 v3, vcc, 0, v1, vcc
	flat_atomic_add v1, v[2:3], v249 offset:1024 sc0
	v_cvt_f32_u32_e32 v2, v0
	v_sub_u32_e32 v3, 0, v0
	s_mov_b64 s[6:7], 0
	v_rcp_iflag_f32_e32 v2, v2
	s_nop 0
	v_mul_f32_e32 v2, 0x4f7ffffe, v2
	v_cvt_u32_f32_e32 v2, v2
	v_mul_lo_u32 v3, v3, v2
	v_mul_hi_u32 v3, v2, v3
	v_add_u32_e32 v2, v2, v3
	s_waitcnt vmcnt(0) lgkmcnt(0)
	v_mul_hi_u32 v2, v1, v2
	v_mul_lo_u32 v3, v2, v0
	v_sub_u32_e32 v3, v1, v3
	v_cmp_ge_u32_e32 vcc, v3, v0
	v_add_u32_e32 v4, 1, v2
	s_nop 0
	v_cndmask_b32_e32 v2, v2, v4, vcc
	v_sub_u32_e32 v4, v3, v0
	v_cndmask_b32_e32 v3, v3, v4, vcc
	v_cmp_ge_u32_e32 vcc, v3, v0
	v_add_u32_e32 v3, 1, v2
	s_nop 0
	v_cndmask_b32_e32 v2, v2, v3, vcc
	v_add_u32_e32 v3, 1, v1
	v_mad_u64_u32 v[0:1], s[2:3], v0, v2, v[0:1]
	v_mov_b32_e32 v7, v0
	s_add_u32 s2, s62, 0x3400
	s_addc_u32 s3, s63, 0
	v_cmp_ne_u32_e32 vcc, v3, v0
	v_mov_b64_e32 v[0:1], s[2:3]
	s_and_saveexec_b64 s[4:5], vcc
	s_cbranch_execz .LBB0_1877
	v_mov_b64_e32 v[0:1], s[2:3]
	flat_load_dword v0, v[0:1] sc1
	s_mov_b64 s[10:11], 0
	s_waitcnt vmcnt(0) lgkmcnt(0)
	v_cmp_lt_u32_e32 vcc, v0, v7
	s_and_saveexec_b64 s[8:9], vcc
	s_cbranch_execz .LBB0_1876
	s_add_u32 s6, s62, 0x200
	s_addc_u32 s7, s63, 0
	s_mov_b32 s1, 1
	s_branch .LBB0_1869

.LBB0_1968:
	s_lshl_b32 s0, s0, 6
	s_add_i32 s38, s0, 0x500
	s_lshl_b64 s[2:3], s[38:39], 2
	s_add_u32 s2, s60, s2
	s_addc_u32 s3, s61, s3
	v_mov_b64_e32 v[4:5], s[2:3]
	flat_atomic_add v3, v[4:5], v249 sc0
	buffer_inv sc1
	v_cvt_f32_u32_e32 v1, v2
	v_sub_u32_e32 v4, 0, v2
	v_rcp_iflag_f32_e32 v1, v1
	s_nop 0
	v_mul_f32_e32 v1, 0x4f7ffffe, v1
	v_cvt_u32_f32_e32 v1, v1
	v_mul_lo_u32 v4, v4, v1
	v_mul_hi_u32 v4, v1, v4
	v_add_u32_e32 v1, v1, v4
	s_waitcnt vmcnt(0) lgkmcnt(0)
	v_mul_hi_u32 v1, v3, v1
	v_mul_lo_u32 v4, v1, v2
	v_sub_u32_e32 v4, v3, v4
	v_cmp_ge_u32_e32 vcc, v4, v2
	v_add_u32_e32 v5, 1, v1
	s_nop 0
	v_cndmask_b32_e32 v1, v1, v5, vcc
	v_sub_u32_e32 v5, v4, v2
	v_cndmask_b32_e32 v4, v4, v5, vcc
	v_cmp_ge_u32_e32 vcc, v4, v2
	v_add_u32_e32 v4, 1, v1
	s_nop 0
	v_cndmask_b32_e32 v1, v1, v4, vcc
	v_add_u32_e32 v4, 1, v3
	v_mad_u64_u32 v[2:3], s[2:3], v2, v1, v[2:3]
	v_cmp_ne_u32_e32 vcc, v4, v2
	s_and_saveexec_b64 s[2:3], vcc
	s_xor_b64 s[2:3], exec, s[2:3]
	s_cbranch_execz .LBB0_1981
	s_movk_i32 s38, 0xd00
	s_lshl_b64 s[4:5], s[38:39], 2
	s_add_u32 s6, s60, s4
	s_addc_u32 s7, s61, s5
	v_mov_b64_e32 v[2:3], s[6:7]
	v_add_u32_e32 v7, 1, v1
	v_mul_lo_u32 v7, v7, v0
	flat_load_dword v0, v[2:3] sc1
	s_waitcnt vmcnt(0) lgkmcnt(0)
	v_cmp_lt_u32_e32 vcc, v0, v7
	s_and_saveexec_b64 s[4:5], vcc
	s_cbranch_execz .LBB0_1980
	s_mov_b32 s1, 1
	s_mov_b64 s[8:9], 0
	s_branch .LBB0_1972

.LBB0_1981:
	s_or_saveexec_b64 s[2:3], s[2:3]
	v_mov_b32_e32 v249, 1
	s_xor_b64 exec, exec, s[2:3]
	s_cbranch_execz .LBB0_1997
	v_mov_b32_e32 v1, s60
	v_add_co_u32_e32 v2, vcc, 0x3000, v1
	v_mov_b32_e32 v1, s61
	buffer_wbl2 sc1
	s_waitcnt vmcnt(0)
	v_addc_co_u32_e32 v3, vcc, 0, v1, vcc
	v_mov_b32_e32 v5, 1
	flat_atomic_add v1, v[2:3], v5 offset:1024 sc0
	v_cvt_f32_u32_e32 v2, v0
	v_sub_u32_e32 v3, 0, v0
	s_mov_b64 s[6:7], 0
	v_rcp_iflag_f32_e32 v2, v2
	s_nop 0
	v_mul_f32_e32 v2, 0x4f7ffffe, v2
	v_cvt_u32_f32_e32 v2, v2
	v_mul_lo_u32 v3, v3, v2
	v_mul_hi_u32 v3, v2, v3
	v_add_u32_e32 v2, v2, v3
	s_waitcnt vmcnt(0) lgkmcnt(0)
	v_mul_hi_u32 v2, v1, v2
	v_mul_lo_u32 v3, v2, v0
	v_sub_u32_e32 v3, v1, v3
	v_cmp_ge_u32_e32 vcc, v3, v0
	v_add_u32_e32 v4, 1, v2
	s_nop 0
	v_cndmask_b32_e32 v2, v2, v4, vcc
	v_sub_u32_e32 v4, v3, v0
	v_cndmask_b32_e32 v3, v3, v4, vcc
	v_cmp_ge_u32_e32 vcc, v3, v0
	v_add_u32_e32 v3, 1, v2
	s_nop 0
	v_cndmask_b32_e32 v2, v2, v3, vcc
	v_add_u32_e32 v3, 1, v1
	v_mad_u64_u32 v[0:1], s[2:3], v0, v2, v[0:1]
	v_mov_b32_e32 v7, v0
	s_add_u32 s2, s60, 0x3400
	s_addc_u32 s3, s61, 0
	v_cmp_ne_u32_e32 vcc, v3, v0
	v_mov_b64_e32 v[0:1], s[2:3]
	s_and_saveexec_b64 s[4:5], vcc
	s_cbranch_execz .LBB0_1994
	v_mov_b64_e32 v[0:1], s[2:3]
	flat_load_dword v0, v[0:1] sc1
	s_mov_b64 s[10:11], 0
	s_waitcnt vmcnt(0) lgkmcnt(0)
	v_cmp_lt_u32_e32 vcc, v0, v7
	s_and_saveexec_b64 s[8:9], vcc
	s_cbranch_execz .LBB0_1993
	s_add_u32 s6, s60, 0x200
	s_addc_u32 s7, s61, 0
	s_mov_b32 s1, 1
	s_branch .LBB0_1986

.LBB0_2176:
	v_mov_b32_e32 v1, s34
	v_add_co_u32_e32 v2, vcc, 0x3000, v1
	v_mov_b32_e32 v1, s35
	buffer_wbl2 sc1
	s_waitcnt vmcnt(0)
	v_addc_co_u32_e32 v3, vcc, 0, v1, vcc
	flat_atomic_add v1, v[2:3], v249 offset:1024 sc0
	v_cvt_f32_u32_e32 v2, v0
	v_sub_u32_e32 v3, 0, v0
	s_mov_b64 s[4:5], 0
	v_rcp_iflag_f32_e32 v2, v2
	s_nop 0
	v_mul_f32_e32 v2, 0x4f7ffffe, v2
	v_cvt_u32_f32_e32 v2, v2
	v_mul_lo_u32 v3, v3, v2
	v_mul_hi_u32 v3, v2, v3
	v_add_u32_e32 v2, v2, v3
	s_waitcnt vmcnt(0) lgkmcnt(0)
	v_mul_hi_u32 v2, v1, v2
	v_mul_lo_u32 v3, v2, v0
	v_sub_u32_e32 v3, v1, v3
	v_cmp_ge_u32_e32 vcc, v3, v0
	v_add_u32_e32 v4, 1, v2
	s_nop 0
	v_cndmask_b32_e32 v2, v2, v4, vcc
	v_sub_u32_e32 v4, v3, v0
	v_cndmask_b32_e32 v3, v3, v4, vcc
	v_cmp_ge_u32_e32 vcc, v3, v0
	v_add_u32_e32 v3, 1, v2
	s_nop 0
	v_cndmask_b32_e32 v2, v2, v3, vcc
	v_add_u32_e32 v3, 1, v1
	v_mad_u64_u32 v[0:1], s[0:1], v0, v2, v[0:1]
	v_mov_b32_e32 v7, v0
	s_add_u32 s0, s34, 0x3400
	s_addc_u32 s1, s35, 0
	v_cmp_ne_u32_e32 vcc, v3, v0
	v_mov_b64_e32 v[0:1], s[0:1]
	s_and_saveexec_b64 s[2:3], vcc
	s_cbranch_execz .LBB0_2188
	v_mov_b64_e32 v[0:1], s[0:1]
	flat_load_dword v0, v[0:1] sc1
	s_mov_b64 s[8:9], 0
	s_waitcnt vmcnt(0) lgkmcnt(0)
	v_cmp_lt_u32_e32 vcc, v0, v7
	s_and_saveexec_b64 s[6:7], vcc
	s_cbranch_execz .LBB0_2187
	s_add_u32 s4, s34, 0x200
	s_addc_u32 s5, s35, 0
	s_mov_b32 s21, 1
	s_branch .LBB0_2180
